# GEMM operand staging: new LDS image so each LDS-DMA instruction fetches 8 rows x 128B full lines (XOR-swizzled 16B slots, two fragment base registers)
# speedup vs baseline: 1.0050x; 1.0050x over previous
; __device__ __forceinline__ int tid_fresh() { int t = threadIdx.x; asm volatile("" : "+v"(t)); return t; }
; #define PG8_STAGE(bufoff, gbase, voff) do { _Pragma("unroll") for (int _i = 0; _i < 2; ++_i) \
;         __builtin_amdgcn_global_load_lds((const unsigned*)((const char*)(gbase) + (voff)[_i]), (LAS unsigned*)(lds + (bufoff) + ldsw + _i * 8192), 16, 0, 0); } while (0)
; #define PG8_WAIT_V(n) asm volatile("s_waitcnt vmcnt(" #n ")" ::: "memory")
; template <class Epi>
; __device__ __forceinline__ void gemm_phase(LAS unsigned char* lds, const Gemm g, const StaticOrder& S, const Epi& E) {
;     const int tid = tid_fresh(), wid = __builtin_amdgcn_readfirstlane(tid >> 6), lane = tid & 63, wr = wid >> 2, wc = wid & 3, fr = lane & 15, fq = lane >> 4;
;     const int K = g.K, nt = K / BK, lda = g.lda;
;     unsigned voffA[2], voffB[2];
; #pragma unroll
;     for (int i = 0; i < 2; ++i) { int R, C; stage_rc(tid * 16 + i * 8192, R, C); const int Rb = Epi::PERM ? ((R & ~31) + perm32(R & 31)) : R;
;         voffA[i] = (unsigned)(R * lda + C) * 2u; voffB[i] = (unsigned)(Rb * K + C) * 2u; }
;     const size_t kstep = (size_t)(BK * 2);
;     const size_t hA = (size_t)HALF * lda * 2, hB = (size_t)HALF * K * 2;
;     const size_t tA = 2 * hA, tB = 2 * hB;
;     const unsigned ldsw = (unsigned)wid * 1024u;
;     const int aoff = lds_byte(wr * 64 + fr, fq * 8), boff = lds_byte(wc * 32 + fr, fq * 8);
;     ...
;     Unit cur, nxt; int ui = 0;
;     if (!S.next(0, cur)) return;
;     f32x4 acc[2][2][4][2];
; #pragma unroll
;     for (int a = 0; a < 2; ++a)
; #pragma unroll
;         for (int b = 0; b < 2; ++b)
; #pragma unroll
;             for (int m = 0; m < 4; ++m)
; #pragma unroll
;                 for (int n = 0; n < 2; ++n) acc[a][b][m][n] = (f32x4){0.f, 0.f, 0.f, 0.f};
;     bf16x8 At[4][2], B0[2][2], B1[2][2];
;     const char* cA = (const char*)g.A + (size_t)cur.pm * tA + (g.agrp ? (size_t)(cur.pn >> 1) * 1024 : 0);
;     const char* cB = (const char*)g.Bt + (size_t)cur.pn * tB;
;     PG8_STAGE(PG8_SB(0, 0), cB, voffB); PG8_STAGE(PG8_SB(0, 1), cB + hB, voffB); PG8_STAGE(PG8_SA(0, 0), cA, voffA); PG8_STAGE(PG8_SA(0, 1), cA + hA, voffA);
;     if (wr == 1) PG8_BAR;
;     PG8_WAIT_V(2); PG8_BAR;
;     PG8_STAGE(PG8_SB(1, 0), cB + kstep, voffB); PG8_STAGE(PG8_SA(1, 0), cA + kstep, voffA); PG8_STAGE(PG8_SB(1, 1), cB + hB + kstep, voffB);
;     PG8_WAIT_V(6); PG8_BAR;
.LBB0_325:
	s_andn2_b64 vcc, exec, s[0:1]
	s_cbranch_vccnz .LBB0_397
	v_bfe_i32 v2, v15, 27, 1
	v_lshlrev_b32_e32 v0, 4, v15
	v_lshrrev_b32_e32 v2, 22, v2
	v_add_u32_e32 v2, v0, v2
	v_and_b32_e32 v2, 0xfffffc00, v2
	v_sub_u32_e32 v2, v0, v2
	v_ashrrev_i32_e32 v1, 31, v15
	v_lshrrev_b32_e32 v3, 4, v2
	v_lshrrev_b32_e32 v1, 26, v1
	v_bitop3_b32 v3, v3, v2, 32 bitop3:0x6c
	v_ashrrev_i32_e32 v2, 31, v2
	v_add_u32_e32 v1, v15, v1
	v_lshrrev_b32_e32 v2, 26, v2
	v_ashrrev_i32_e32 v1, 6, v1
	v_add_u32_e32 v2, v3, v2
	v_lshlrev_b32_e32 v4, 3, v1
	v_ashrrev_i32_e32 v2, 6, v2
	v_lshlrev_b32_e32 v1, 5, v1
	v_and_b32_e32 v4, 0x7ffffff0, v4
	v_and_b32_e32 v12, 32, v1
	v_mul_i32_i24_e32 v1, 64, v2
	v_add_u32_e32 v4, v2, v4
	v_sub_u32_e32 v1, v3, v1
	v_ashrrev_i16_sdwa v1, v203, sext(v1) dst_sel:DWORD dst_unused:UNUSED_PAD src0_sel:DWORD src1_sel:BYTE_0
	v_mul_lo_u32 v14, v4, s7
	v_bfe_i32 v13, v1, 0, 16
	v_or_b32_e32 v1, v14, v12
	v_add_u32_e32 v0, 0x2000, v0
	v_add_lshl_u32 v168, v1, v13, 1
	v_ashrrev_i32_e32 v1, 31, v0
	v_lshrrev_b32_e32 v1, 22, v1
	v_add_u32_e32 v1, v0, v1
	s_lshl_b32 s16, s7, 8
	s_mov_b32 s17, s3
	v_ashrrev_i32_e32 v1, 10, v1
	s_lshl_b64 s[18:19], s[16:17], 1
	s_ashr_i32 s4, s55, 31
	v_mul_i32_i24_e32 v2, 0x400, v1
	s_mul_i32 s4, s18, s4
	s_mul_hi_u32 s5, s18, s55
	v_sub_u32_e32 v0, v0, v2
	s_add_i32 s4, s5, s4
	s_bfe_u32 s5, s7, 0x10017
	v_lshrrev_b32_e32 v2, 4, v0
	s_mul_i32 s20, s5, s55
	v_bitop3_b32 v0, v2, v0, 32 bitop3:0x6c
	s_add_i32 s20, s4, s20
	s_ashr_i32 s4, s2, 31
	v_ashrrev_i32_e32 v3, 31, v0
	s_mul_i32 s4, s18, s4
	s_mul_hi_u32 s22, s18, s2
	s_ashr_i32 s0, s6, 6
	v_lshrrev_b32_e32 v3, 26, v3
	s_add_i32 s4, s22, s4
	s_mul_i32 s5, s5, s2
	v_lshlrev_b32_e32 v2, 3, v1
	v_add_u32_e32 v3, v0, v3
	v_lshlrev_b32_e32 v1, 5, v1
	s_ashr_i32 s1, s6, 8
	s_lshl_b32 s41, s0, 10
	s_add_i32 s4, s4, s5
	s_mul_i32 s5, s18, s2
	v_and_b32_e32 v2, 0x7ffffff0, v2
	v_ashrrev_i32_e32 v4, 6, v3
	v_and_b32_e32 v16, 32, v1
	v_and_b32_e32 v1, 0xc0, v3
	s_add_u32 s34, s12, s5
	v_add_u32_e32 v2, v4, v2
	v_sub_u32_e32 v0, v0, v1
	s_addc_u32 s35, s13, s4
	s_add_i32 s42, s41, 0
	v_ashrrev_i16_sdwa v0, v203, sext(v0) dst_sel:DWORD dst_unused:UNUSED_PAD src0_sel:DWORD src1_sel:BYTE_0
	s_waitcnt vmcnt(3)
	v_mul_lo_u32 v18, v2, s7
	s_add_i32 m0, s42, 0x10000
	v_bfe_i32 v17, v0, 0, 16
	v_lshrrev_b32_e32 v128, 3, v167
	v_and_b32_e32 v129, 7, v167
	v_xor_b32_e32 v129, v129, v128
	v_lshlrev_b32_e32 v129, 4, v129
	v_lshl_add_u32 v130, s0, 3, v128
	v_mov_b32_e32 v134, s7
	v_lshlrev_b32_e32 v134, 1, v134
	v_mul_lo_u32 v135, v130, v134
	v_add_u32_e32 v168, v135, v129
	v_lshl_add_u32 v248, v134, 6, v168
	v_and_b32_e32 v128, 7, v167
	v_lshrrev_b32_e32 v129, 4, v167
	v_bfe_u32 v130, v167, 3, 1
	v_xor_b32_e32 v129, v129, v128
	v_lshlrev_b32_e32 v128, 7, v128
	v_lshl_add_u32 v128, v130, 10, v128
	v_lshl_add_u32 v250, v129, 4, v128
	v_or_b32_e32 v0, v18, v16
	global_load_lds_dwordx4 v168, s[34:35]
	s_add_i32 m0, s42, 0x12000
	v_add_lshl_u32 v174, v0, v17, 1
	v_mov_b32_e32 v174, v248
	s_add_u32 s4, s34, s16
	global_load_lds_dwordx4 v174, s[34:35]
	s_addc_u32 s5, s35, 0
	s_add_i32 m0, s42, 0x14000
	s_mul_i32 s21, s18, s55
	global_load_lds_dwordx4 v168, s[4:5]
	s_add_i32 m0, s42, 0x16000
	s_add_u32 s36, s8, s21
	v_mov_b32_e32 v175, v169
	s_addc_u32 s37, s9, s20
	s_add_i32 s43, s42, 0x2000
	v_lshl_add_u64 v[4:5], s[4:5], 0, v[168:169]
	v_lshl_add_u64 v[6:7], s[4:5], 0, v[174:175]
	global_load_lds_dwordx4 v174, s[4:5]
	s_mov_b32 m0, s42
	s_add_u32 s4, s36, s16
	global_load_lds_dwordx4 v168, s[36:37]
	s_mov_b32 m0, s43
	s_addc_u32 s5, s37, 0
	s_add_i32 s44, s42, 0x4000
	global_load_lds_dwordx4 v174, s[36:37]
	s_mov_b32 m0, s44
	s_add_i32 s45, s42, 0x6000
	global_load_lds_dwordx4 v168, s[4:5]
	s_mov_b32 m0, s45
	s_cmp_eq_u32 s1, 1
	global_load_lds_dwordx4 v174, s[4:5]
	v_lshl_add_u64 v[0:1], s[34:35], 0, v[168:169]
	v_lshl_add_u64 v[2:3], s[34:35], 0, v[174:175]
	v_lshl_add_u64 v[8:9], s[36:37], 0, v[168:169]
	v_lshl_add_u64 v[10:11], s[36:37], 0, v[174:175]
	s_cselect_b64 s[20:21], -1, 0
	s_cmp_lg_u32 s1, 1
	s_cbranch_scc1 .LBB0_328
	s_barrier
.LBB0_328:
	v_bfe_u32 v19, v15, 4, 2
	v_and_b32_e32 v20, 15, v15
	v_lshlrev_b32_e32 v21, 4, v19
	v_lshlrev_b32_e32 v15, 2, v15
	s_and_b32 s46, s0, 3
	v_lshl_or_b32 v188, s1, 6, v20
	v_lshl_or_b32 v20, v20, 6, v21
	s_lshl_b32 s0, s1, 13
	v_and_b32_e32 v15, 32, v15
	s_lshr_b32 s47, s7, 6
	v_bitop3_b32 v21, v20, s0, v15 bitop3:0xde
	s_lshl_b32 s0, s46, 12
	s_add_u32 s22, s74, 0x17784000
	s_addc_u32 s23, s75, 0
	s_add_i32 m0, s42, 0x18000
	v_lshl_add_u64 v[0:1], v[0:1], 0, s[80:81]
	s_waitcnt vmcnt(2)
	s_barrier
	global_load_lds_dwordx4 v[0:1], off
	v_lshl_add_u64 v[0:1], v[2:3], 0, s[80:81]
	s_add_i32 m0, s42, 0x1a000
	s_add_i32 s48, s42, 0x8000
	global_load_lds_dwordx4 v[0:1], off
	v_lshl_add_u64 v[0:1], v[8:9], 0, s[80:81]
	s_mov_b32 m0, s48
	s_add_i32 s49, s42, 0xa000
	global_load_lds_dwordx4 v[0:1], off
	v_lshl_add_u64 v[0:1], v[10:11], 0, s[80:81]
	s_mov_b32 m0, s49
	s_add_i32 s50, s47, -2
	global_load_lds_dwordx4 v[0:1], off
	s_add_i32 m0, s42, 0x1c000
	v_lshl_add_u64 v[0:1], v[4:5], 0, s[80:81]
	global_load_lds_dwordx4 v[0:1], off
	v_lshl_add_u64 v[0:1], v[6:7], 0, s[80:81]
	s_add_i32 m0, s42, 0x1e000
	s_cmpk_lt_u32 s6, 0x100
	global_load_lds_dwordx4 v[0:1], off
	v_lshlrev_b32_e32 v0, 2, v19
	v_lshl_or_b32 v190, s46, 5, v0
	v_add_u32_e32 v0, v14, v12
	v_add_lshl_u32 v0, v0, v13, 1
	v_mov_b32_e32 v1, v169
	s_waitcnt vmcnt(6)
	s_cselect_b64 s[24:25], -1, 0
	s_ashr_i32 s52, s39, 31
	s_ashr_i32 s53, s40, 31
	v_lshl_add_u64 v[176:177], s[16:17], 0, v[0:1]
	v_add_u32_e32 v176, s16, v168
	v_mov_b32_e32 v177, v169
	v_add_u32_e32 v0, v18, v16
	s_cmp_lg_u64 s[10:11], 0
	v_add_lshl_u32 v0, v0, v17, 1
	v_bitop3_b32 v189, v20, s0, v15 bitop3:0xde
	v_add_u32_e32 v240, 0x10000, v189
	v_lshl_add_u32 v240, s46, 12, v250
	v_add_u32_e32 v240, 0x10000, v240
	v_xor_b32_e32 v252, 64, v240
	v_lshl_add_u32 v253, s1, 13, v250
	v_add_u32_e32 v241, 0x80, v168
	v_add_u32_e32 v242, 0x80, v174
	s_mov_b32 s51, 0
	v_cmp_eq_u32_e64 s[0:1], 0, v19
	s_cselect_b64 s[26:27], -1, 0
	v_lshl_add_u64 v[178:179], s[16:17], 0, v[0:1]
	v_add_u32_e32 v178, s16, v174
	v_mov_b32_e32 v179, v169
	v_add_u32_e32 v191, 0, v21
	v_mov_b32_e32 v191, v253
	v_xor_b32_e32 v251, 64, v191
	s_barrier
	s_branch .LBB0_331

; #define PG8_STAGE(bufoff, gbase, voff) do { _Pragma("unroll") for (int _i = 0; _i < 2; ++_i) \
;         __builtin_amdgcn_global_load_lds((const unsigned*)((const char*)(gbase) + (voff)[_i]), (LAS unsigned*)(lds + (bufoff) + ldsw + _i * 8192), 16, 0, 0); } while (0)
; #define PG8_LDA(dst, b, h) do { _Pragma("unroll") for (int m = 0; m < 4; ++m) _Pragma("unroll") for (int k = 0; k < 2; ++k) dst[m][k] = *(const LAS bf16x8*)(lds + PG8_SA(b, h) + aoff + m * 2048 + k * 1024); } while (0)
; #define PG8_LDB(dst, b, h) do { _Pragma("unroll") for (int n = 0; n < 2; ++n) _Pragma("unroll") for (int k = 0; k < 2; ++k) dst[n][k] = *(const LAS bf16x8*)(lds + PG8_SB(b, h) + boff + n * 2048 + k * 1024); } while (0)
; #define PG8_MMA(ai, bj, At, Bt) do { __builtin_amdgcn_s_setprio(1); _Pragma("unroll") for (int m = 0; m < 4; ++m) _Pragma("unroll") for (int n = 0; n < 2; ++n) _Pragma("unroll") for (int k = 0; k < 2; ++k) \
;         acc[ai][bj][m][n] = __builtin_amdgcn_mfma_f32_16x16x32_bf16(Bt[n][k], At[m][k], acc[ai][bj][m][n], 0, 0, 0); __builtin_amdgcn_s_setprio(0); } while (0)
; #define PG8_WAIT_V(n) asm volatile("s_waitcnt vmcnt(" #n ")" ::: "memory")
; #define PG8_WAIT_L(n) asm volatile("s_waitcnt lgkmcnt(" #n ")" ::: "memory")
; #define PG8_BAR __builtin_amdgcn_s_barrier()
; #define PG8_SCHED __builtin_amdgcn_sched_barrier(0)
; template <class Epi>
; __device__ __forceinline__ void gemm_phase(LAS unsigned char* lds, const Gemm g, const StaticOrder& S, const Epi& E) {
;     ...
;             PG8_LDB(B0, 0, 0); PG8_LDB(B1, 0, 1); PG8_SCHED; PG8_LDA(At, 0, 0); PG8_STAGE(PG8_SA(1, 1), a1 + hA, voffA);
;             PG8_WAIT_V(8); PG8_WAIT_L(0); PG8_BAR; PG8_MMA(0, 0, At, B0); PG8_MMA(0, 1, At, B1); PG8_BAR; PG8_SCHED;
;             PG8_LDA(At, 0, 1); PG8_STAGE(PG8_SB(0, 0), b2, voffB); PG8_STAGE(PG8_SB(0, 1), b2 + hB, voffB); PG8_STAGE(PG8_SA(0, 0), a2, voffA);
;             PG8_WAIT_V(8); PG8_WAIT_L(0); PG8_BAR; PG8_MMA(1, 0, At, B0); PG8_MMA(1, 1, At, B1); PG8_BAR; PG8_SCHED;
.LBB0_342:
	s_add_i32 m0, s42, 0xc000
	ds_read_b128 v[128:131], v240
	ds_read_b128 v[132:135], v252
	ds_read_b128 v[136:139], v240 offset:2048
	ds_read_b128 v[140:143], v252 offset:2048
	ds_read_b128 v[144:147], v240 offset:16384
	ds_read_b128 v[148:151], v252 offset:16384
	ds_read_b128 v[152:155], v240 offset:18432
	ds_read_b128 v[156:159], v252 offset:18432
	ds_read_b128 v[160:163], v191
	ds_read_b128 v[180:183], v251
	ds_read_b128 v[184:187], v191 offset:2048
	ds_read_b128 v[192:195], v251 offset:2048
	ds_read_b128 v[206:209], v191 offset:4096
	ds_read_b128 v[210:213], v251 offset:4096
	ds_read_b128 v[214:217], v191 offset:6144
	ds_read_b128 v[218:221], v251 offset:6144
	global_load_lds_dwordx4 v176, s[4:5]
	s_add_i32 m0, s42, 0xe000
	s_nop 0
	global_load_lds_dwordx4 v178, s[4:5]
	s_add_i32 s56, s34, 2
	s_add_u32 s57, s4, 0x80
	s_addc_u32 s35, s5, 0
	s_add_i32 s60, 0, 0x10000
	s_cmp_eq_u32 s50, s34
	s_cselect_b32 s35, s29, s35
	s_cselect_b32 s34, s28, s57
	s_cselect_b32 s59, s31, s37
	s_cselect_b32 s58, s30, s36
	s_add_i32 s57, 0, 0x14000
	s_waitcnt vmcnt(8)
	s_waitcnt lgkmcnt(0)
	s_barrier
	s_setprio 1
	s_waitcnt lgkmcnt(0)
	v_mfma_f32_16x16x32_bf16 v[124:127], v[128:131], v[160:163], v[124:127]
	v_mfma_f32_16x16x32_bf16 v[120:123], v[136:139], v[160:163], v[120:123]
	v_mfma_f32_16x16x32_bf16 v[112:115], v[128:131], v[184:187], v[112:115]
	v_mfma_f32_16x16x32_bf16 v[104:107], v[136:139], v[184:187], v[104:107]
	v_mfma_f32_16x16x32_bf16 v[96:99], v[128:131], v[206:209], v[96:99]
	v_mfma_f32_16x16x32_bf16 v[88:91], v[136:139], v[206:209], v[88:91]
	v_mfma_f32_16x16x32_bf16 v[80:83], v[128:131], v[214:217], v[80:83]
	v_mfma_f32_16x16x32_bf16 v[72:75], v[136:139], v[214:217], v[72:75]
	v_mfma_f32_16x16x32_bf16 v[124:127], v[132:135], v[180:183], v[124:127]
	v_mfma_f32_16x16x32_bf16 v[120:123], v[140:143], v[180:183], v[120:123]
	v_mfma_f32_16x16x32_bf16 v[112:115], v[132:135], v[192:195], v[112:115]
	v_mfma_f32_16x16x32_bf16 v[104:107], v[140:143], v[192:195], v[104:107]
	v_mfma_f32_16x16x32_bf16 v[96:99], v[132:135], v[210:213], v[96:99]
	v_mfma_f32_16x16x32_bf16 v[88:91], v[140:143], v[210:213], v[88:91]
	v_mfma_f32_16x16x32_bf16 v[80:83], v[132:135], v[218:221], v[80:83]
	v_mfma_f32_16x16x32_bf16 v[72:75], v[140:143], v[218:221], v[72:75]
	s_setprio 0
	s_setprio 1
	v_mfma_f32_16x16x32_bf16 v[116:119], v[144:147], v[160:163], v[116:119]
	v_mfma_f32_16x16x32_bf16 v[108:111], v[152:155], v[160:163], v[108:111]
	v_mfma_f32_16x16x32_bf16 v[100:103], v[144:147], v[184:187], v[100:103]
	v_mfma_f32_16x16x32_bf16 v[92:95], v[152:155], v[184:187], v[92:95]
	v_mfma_f32_16x16x32_bf16 v[84:87], v[144:147], v[206:209], v[84:87]
	v_mfma_f32_16x16x32_bf16 v[76:79], v[152:155], v[206:209], v[76:79]
	v_mfma_f32_16x16x32_bf16 v[68:71], v[144:147], v[214:217], v[68:71]
	v_mfma_f32_16x16x32_bf16 v[64:67], v[152:155], v[214:217], v[64:67]
	v_mfma_f32_16x16x32_bf16 v[116:119], v[148:151], v[180:183], v[116:119]
	v_mfma_f32_16x16x32_bf16 v[108:111], v[156:159], v[180:183], v[108:111]
	v_mfma_f32_16x16x32_bf16 v[100:103], v[148:151], v[192:195], v[100:103]
	v_mfma_f32_16x16x32_bf16 v[92:95], v[156:159], v[192:195], v[92:95]
	v_mfma_f32_16x16x32_bf16 v[84:87], v[148:151], v[210:213], v[84:87]
	v_mfma_f32_16x16x32_bf16 v[76:79], v[156:159], v[210:213], v[76:79]
	v_mfma_f32_16x16x32_bf16 v[68:71], v[148:151], v[218:221], v[68:71]
	v_mfma_f32_16x16x32_bf16 v[64:67], v[156:159], v[218:221], v[64:67]
	s_setprio 0
	s_barrier
	ds_read_b128 v[160:163], v191 offset:16384
	ds_read_b128 v[180:183], v251 offset:16384
	ds_read_b128 v[184:187], v191 offset:18432
	ds_read_b128 v[192:195], v251 offset:18432
	ds_read_b128 v[206:209], v191 offset:20480
	ds_read_b128 v[210:213], v251 offset:20480
	ds_read_b128 v[214:217], v191 offset:22528
	ds_read_b128 v[218:221], v251 offset:22528
	s_add_i32 s60, s60, s41
	s_mov_b32 m0, s60
	s_add_i32 s57, s57, s41
	global_load_lds_dwordx4 v168, s[58:59]
	s_add_i32 m0, s60, 0x2000
	s_nop 0
	global_load_lds_dwordx4 v174, s[58:59]
	s_add_u32 s58, s58, s16
	s_addc_u32 s59, s59, 0
	s_mov_b32 m0, s57
	s_nop 0
	global_load_lds_dwordx4 v168, s[58:59]
	s_add_i32 m0, s57, 0x2000
	s_nop 0
	global_load_lds_dwordx4 v174, s[58:59]
	s_mov_b32 m0, s42
	s_nop 0
	global_load_lds_dwordx4 v168, s[34:35]
	s_mov_b32 m0, s43
	s_nop 0
	global_load_lds_dwordx4 v174, s[34:35]
	s_waitcnt vmcnt(8)
	s_waitcnt lgkmcnt(0)
	s_barrier
	s_setprio 1
	s_waitcnt lgkmcnt(0)
	v_mfma_f32_16x16x32_bf16 v[60:63], v[128:131], v[160:163], v[60:63]
	v_mfma_f32_16x16x32_bf16 v[56:59], v[136:139], v[160:163], v[56:59]
	v_mfma_f32_16x16x32_bf16 v[48:51], v[128:131], v[184:187], v[48:51]
	v_mfma_f32_16x16x32_bf16 v[40:43], v[136:139], v[184:187], v[40:43]
	v_mfma_f32_16x16x32_bf16 v[32:35], v[128:131], v[206:209], v[32:35]
	v_mfma_f32_16x16x32_bf16 v[24:27], v[136:139], v[206:209], v[24:27]
	v_mfma_f32_16x16x32_bf16 v[16:19], v[128:131], v[214:217], v[16:19]
	v_mfma_f32_16x16x32_bf16 v[8:11], v[136:139], v[214:217], v[8:11]
	v_mfma_f32_16x16x32_bf16 v[60:63], v[132:135], v[180:183], v[60:63]
	v_mfma_f32_16x16x32_bf16 v[56:59], v[140:143], v[180:183], v[56:59]
	v_mfma_f32_16x16x32_bf16 v[48:51], v[132:135], v[192:195], v[48:51]
	v_mfma_f32_16x16x32_bf16 v[40:43], v[140:143], v[192:195], v[40:43]
	v_mfma_f32_16x16x32_bf16 v[32:35], v[132:135], v[210:213], v[32:35]
	v_mfma_f32_16x16x32_bf16 v[24:27], v[140:143], v[210:213], v[24:27]
	v_mfma_f32_16x16x32_bf16 v[16:19], v[132:135], v[218:221], v[16:19]
	v_mfma_f32_16x16x32_bf16 v[8:11], v[140:143], v[218:221], v[8:11]
	s_setprio 0
	s_setprio 1
	v_mfma_f32_16x16x32_bf16 v[52:55], v[144:147], v[160:163], v[52:55]
	v_mfma_f32_16x16x32_bf16 v[44:47], v[152:155], v[160:163], v[44:47]
	v_mfma_f32_16x16x32_bf16 v[36:39], v[144:147], v[184:187], v[36:39]
	v_mfma_f32_16x16x32_bf16 v[28:31], v[152:155], v[184:187], v[28:31]
	v_mfma_f32_16x16x32_bf16 v[20:23], v[144:147], v[206:209], v[20:23]
	v_mfma_f32_16x16x32_bf16 v[12:15], v[152:155], v[206:209], v[12:15]
	v_mfma_f32_16x16x32_bf16 v[4:7], v[144:147], v[214:217], v[4:7]
	v_mfma_f32_16x16x32_bf16 v[0:3], v[152:155], v[214:217], v[0:3]
	v_mfma_f32_16x16x32_bf16 v[52:55], v[148:151], v[180:183], v[52:55]
	v_mfma_f32_16x16x32_bf16 v[44:47], v[156:159], v[180:183], v[44:47]
	v_mfma_f32_16x16x32_bf16 v[36:39], v[148:151], v[192:195], v[36:39]
	v_mfma_f32_16x16x32_bf16 v[28:31], v[156:159], v[192:195], v[28:31]
	v_mfma_f32_16x16x32_bf16 v[20:23], v[148:151], v[210:213], v[20:23]
	v_mfma_f32_16x16x32_bf16 v[12:15], v[156:159], v[210:213], v[12:15]
	v_mfma_f32_16x16x32_bf16 v[4:7], v[148:151], v[218:221], v[4:7]
	v_mfma_f32_16x16x32_bf16 v[0:3], v[156:159], v[218:221], v[0:3]
	s_setprio 0
	s_barrier
; #define PG8_STAGE(bufoff, gbase, voff) do { _Pragma("unroll") for (int _i = 0; _i < 2; ++_i) \
;         __builtin_amdgcn_global_load_lds((const unsigned*)((const char*)(gbase) + (voff)[_i]), (LAS unsigned*)(lds + (bufoff) + ldsw + _i * 8192), 16, 0, 0); } while (0)
; #define PG8_LDA(dst, b, h) do { _Pragma("unroll") for (int m = 0; m < 4; ++m) _Pragma("unroll") for (int k = 0; k < 2; ++k) dst[m][k] = *(const LAS bf16x8*)(lds + PG8_SA(b, h) + aoff + m * 2048 + k * 1024); } while (0)
; #define PG8_LDB(dst, b, h) do { _Pragma("unroll") for (int n = 0; n < 2; ++n) _Pragma("unroll") for (int k = 0; k < 2; ++k) dst[n][k] = *(const LAS bf16x8*)(lds + PG8_SB(b, h) + boff + n * 2048 + k * 1024); } while (0)
; #define PG8_MMA(ai, bj, At, Bt) do { __builtin_amdgcn_s_setprio(1); _Pragma("unroll") for (int m = 0; m < 4; ++m) _Pragma("unroll") for (int n = 0; n < 2; ++n) _Pragma("unroll") for (int k = 0; k < 2; ++k) \
;         acc[ai][bj][m][n] = __builtin_amdgcn_mfma_f32_16x16x32_bf16(Bt[n][k], At[m][k], acc[ai][bj][m][n], 0, 0, 0); __builtin_amdgcn_s_setprio(0); } while (0)
; #define PG8_WAIT_V(n) asm volatile("s_waitcnt vmcnt(" #n ")" ::: "memory")
; #define PG8_WAIT_L(n) asm volatile("s_waitcnt lgkmcnt(" #n ")" ::: "memory")
; #define PG8_BAR __builtin_amdgcn_s_barrier()
; #define PG8_SCHED __builtin_amdgcn_sched_barrier(0)
; template <class Epi>
; __device__ __forceinline__ void gemm_phase(LAS unsigned char* lds, const Gemm g, const StaticOrder& S, const Epi& E) {
;     ...
;             PG8_LDB(B0, 1, 0); PG8_LDB(B1, 1, 1); PG8_SCHED; PG8_LDA(At, 1, 0); PG8_STAGE(PG8_SA(0, 1), a2 + hA, voffA);
;             PG8_WAIT_V(8); PG8_WAIT_L(0); PG8_BAR; PG8_MMA(0, 0, At, B0); PG8_MMA(0, 1, At, B1); PG8_BAR; PG8_SCHED;
;             PG8_LDA(At, 1, 1); PG8_STAGE(PG8_SB(1, 0), b3, voffB); PG8_STAGE(PG8_SB(1, 1), b3 + hB, voffB); PG8_STAGE(PG8_SA(1, 0), a3, voffA);
;             PG8_WAIT_V(8); PG8_WAIT_L(0); PG8_BAR; PG8_MMA(1, 0, At, B0); PG8_MMA(1, 1, At, B1); PG8_BAR; PG8_SCHED;
;         }
	ds_read_b128 v[128:131], v240 offset:32768
	ds_read_b128 v[132:135], v252 offset:32768
	ds_read_b128 v[136:139], v240 offset:34816
	ds_read_b128 v[140:143], v252 offset:34816
	ds_read_b128 v[144:147], v240 offset:49152
	ds_read_b128 v[148:151], v252 offset:49152
	ds_read_b128 v[152:155], v240 offset:51200
	ds_read_b128 v[156:159], v252 offset:51200
	ds_read_b128 v[160:163], v191 offset:32768
	ds_read_b128 v[180:183], v251 offset:32768
	ds_read_b128 v[184:187], v191 offset:34816
	ds_read_b128 v[192:195], v251 offset:34816
	ds_read_b128 v[206:209], v191 offset:36864
	ds_read_b128 v[210:213], v251 offset:36864
	ds_read_b128 v[214:217], v191 offset:38912
	ds_read_b128 v[218:221], v251 offset:38912
	s_add_u32 s34, s34, s16
	s_addc_u32 s35, s35, 0
	s_mov_b32 m0, s44
	s_add_i32 s60, 0, 0x18000
	global_load_lds_dwordx4 v168, s[34:35]
	s_mov_b32 m0, s45
	s_nop 0
	global_load_lds_dwordx4 v174, s[34:35]
	s_waitcnt vmcnt(8)
	s_waitcnt lgkmcnt(0)
	s_barrier
	s_setprio 1
	s_waitcnt lgkmcnt(0)
	v_mfma_f32_16x16x32_bf16 v[124:127], v[128:131], v[160:163], v[124:127]
	v_mfma_f32_16x16x32_bf16 v[120:123], v[136:139], v[160:163], v[120:123]
	v_mfma_f32_16x16x32_bf16 v[112:115], v[128:131], v[184:187], v[112:115]
	v_mfma_f32_16x16x32_bf16 v[104:107], v[136:139], v[184:187], v[104:107]
	v_mfma_f32_16x16x32_bf16 v[96:99], v[128:131], v[206:209], v[96:99]
	v_mfma_f32_16x16x32_bf16 v[88:91], v[136:139], v[206:209], v[88:91]
	v_mfma_f32_16x16x32_bf16 v[80:83], v[128:131], v[214:217], v[80:83]
	v_mfma_f32_16x16x32_bf16 v[72:75], v[136:139], v[214:217], v[72:75]
	v_mfma_f32_16x16x32_bf16 v[124:127], v[132:135], v[180:183], v[124:127]
	v_mfma_f32_16x16x32_bf16 v[120:123], v[140:143], v[180:183], v[120:123]
	v_mfma_f32_16x16x32_bf16 v[112:115], v[132:135], v[192:195], v[112:115]
	v_mfma_f32_16x16x32_bf16 v[104:107], v[140:143], v[192:195], v[104:107]
	v_mfma_f32_16x16x32_bf16 v[96:99], v[132:135], v[210:213], v[96:99]
	v_mfma_f32_16x16x32_bf16 v[88:91], v[140:143], v[210:213], v[88:91]
	v_mfma_f32_16x16x32_bf16 v[80:83], v[132:135], v[218:221], v[80:83]
	v_mfma_f32_16x16x32_bf16 v[72:75], v[140:143], v[218:221], v[72:75]
	s_setprio 0
	s_setprio 1
	v_mfma_f32_16x16x32_bf16 v[116:119], v[144:147], v[160:163], v[116:119]
	v_mfma_f32_16x16x32_bf16 v[108:111], v[152:155], v[160:163], v[108:111]
	v_mfma_f32_16x16x32_bf16 v[100:103], v[144:147], v[184:187], v[100:103]
	v_mfma_f32_16x16x32_bf16 v[92:95], v[152:155], v[184:187], v[92:95]
	v_mfma_f32_16x16x32_bf16 v[84:87], v[144:147], v[206:209], v[84:87]
	v_mfma_f32_16x16x32_bf16 v[76:79], v[152:155], v[206:209], v[76:79]
	v_mfma_f32_16x16x32_bf16 v[68:71], v[144:147], v[214:217], v[68:71]
	v_mfma_f32_16x16x32_bf16 v[64:67], v[152:155], v[214:217], v[64:67]
	v_mfma_f32_16x16x32_bf16 v[116:119], v[148:151], v[180:183], v[116:119]
	v_mfma_f32_16x16x32_bf16 v[108:111], v[156:159], v[180:183], v[108:111]
	v_mfma_f32_16x16x32_bf16 v[100:103], v[148:151], v[192:195], v[100:103]
	v_mfma_f32_16x16x32_bf16 v[92:95], v[156:159], v[192:195], v[92:95]
	v_mfma_f32_16x16x32_bf16 v[84:87], v[148:151], v[210:213], v[84:87]
	v_mfma_f32_16x16x32_bf16 v[76:79], v[156:159], v[210:213], v[76:79]
	v_mfma_f32_16x16x32_bf16 v[68:71], v[148:151], v[218:221], v[68:71]
	v_mfma_f32_16x16x32_bf16 v[64:67], v[156:159], v[218:221], v[64:67]
	s_setprio 0
	s_barrier
	ds_read_b128 v[160:163], v191 offset:49152
	ds_read_b128 v[180:183], v251 offset:49152
	ds_read_b128 v[184:187], v191 offset:51200
	ds_read_b128 v[192:195], v251 offset:51200
	ds_read_b128 v[206:209], v191 offset:53248
	ds_read_b128 v[210:213], v251 offset:53248
	ds_read_b128 v[214:217], v191 offset:55296
	ds_read_b128 v[218:221], v251 offset:55296
	s_add_i32 s60, s60, s41
	s_add_i32 m0, s60, 0x4000
	s_nop 0
	global_load_lds_dwordx4 v241, s[58:59]
	s_add_i32 m0, s60, 0x6000
	s_nop 0
	global_load_lds_dwordx4 v242, s[58:59]
	s_sub_u32 s58, s58, s16
	s_subb_u32 s59, s59, 0
	s_mov_b32 m0, s60
	s_nop 0
	global_load_lds_dwordx4 v241, s[58:59]
	s_add_i32 m0, s60, 0x2000
	s_nop 0
	global_load_lds_dwordx4 v242, s[58:59]
	s_sub_u32 s34, s34, s16
	s_subb_u32 s35, s35, 0
	s_mov_b32 m0, s48
	s_nop 0
	global_load_lds_dwordx4 v241, s[34:35]
	s_mov_b32 m0, s49
	s_nop 0
	global_load_lds_dwordx4 v242, s[34:35]
	s_waitcnt vmcnt(8)
	s_waitcnt lgkmcnt(0)
	s_barrier
	s_setprio 1
	s_waitcnt lgkmcnt(0)
	v_mfma_f32_16x16x32_bf16 v[60:63], v[128:131], v[160:163], v[60:63]
	v_mfma_f32_16x16x32_bf16 v[56:59], v[136:139], v[160:163], v[56:59]
	v_mfma_f32_16x16x32_bf16 v[48:51], v[128:131], v[184:187], v[48:51]
	v_mfma_f32_16x16x32_bf16 v[40:43], v[136:139], v[184:187], v[40:43]
	v_mfma_f32_16x16x32_bf16 v[32:35], v[128:131], v[206:209], v[32:35]
	v_mfma_f32_16x16x32_bf16 v[24:27], v[136:139], v[206:209], v[24:27]
	v_mfma_f32_16x16x32_bf16 v[16:19], v[128:131], v[214:217], v[16:19]
	v_mfma_f32_16x16x32_bf16 v[8:11], v[136:139], v[214:217], v[8:11]
	v_mfma_f32_16x16x32_bf16 v[60:63], v[132:135], v[180:183], v[60:63]
	v_mfma_f32_16x16x32_bf16 v[56:59], v[140:143], v[180:183], v[56:59]
	v_mfma_f32_16x16x32_bf16 v[48:51], v[132:135], v[192:195], v[48:51]
	v_mfma_f32_16x16x32_bf16 v[40:43], v[140:143], v[192:195], v[40:43]
	v_mfma_f32_16x16x32_bf16 v[32:35], v[132:135], v[210:213], v[32:35]
	v_mfma_f32_16x16x32_bf16 v[24:27], v[140:143], v[210:213], v[24:27]
	v_mfma_f32_16x16x32_bf16 v[16:19], v[132:135], v[218:221], v[16:19]
	v_mfma_f32_16x16x32_bf16 v[8:11], v[140:143], v[218:221], v[8:11]
	s_setprio 0
	s_setprio 1
	v_mfma_f32_16x16x32_bf16 v[52:55], v[144:147], v[160:163], v[52:55]
	v_mfma_f32_16x16x32_bf16 v[44:47], v[152:155], v[160:163], v[44:47]
	v_mfma_f32_16x16x32_bf16 v[36:39], v[144:147], v[184:187], v[36:39]
	v_mfma_f32_16x16x32_bf16 v[28:31], v[152:155], v[184:187], v[28:31]
	v_mfma_f32_16x16x32_bf16 v[20:23], v[144:147], v[206:209], v[20:23]
	v_mfma_f32_16x16x32_bf16 v[12:15], v[152:155], v[206:209], v[12:15]
	v_mfma_f32_16x16x32_bf16 v[4:7], v[144:147], v[214:217], v[4:7]
	v_mfma_f32_16x16x32_bf16 v[0:3], v[152:155], v[214:217], v[0:3]
	v_mfma_f32_16x16x32_bf16 v[52:55], v[148:151], v[180:183], v[52:55]
	v_mfma_f32_16x16x32_bf16 v[44:47], v[156:159], v[180:183], v[44:47]
	v_mfma_f32_16x16x32_bf16 v[36:39], v[148:151], v[192:195], v[36:39]
	v_mfma_f32_16x16x32_bf16 v[28:31], v[156:159], v[192:195], v[28:31]
	v_mfma_f32_16x16x32_bf16 v[20:23], v[148:151], v[210:213], v[20:23]
	v_mfma_f32_16x16x32_bf16 v[12:15], v[156:159], v[210:213], v[12:15]
	v_mfma_f32_16x16x32_bf16 v[4:7], v[148:151], v[218:221], v[4:7]
	v_mfma_f32_16x16x32_bf16 v[0:3], v[156:159], v[218:221], v[0:3]
	s_setprio 0
	s_barrier
	s_add_u32 s4, s4, 0x100
	s_addc_u32 s5, s5, 0
	s_add_u32 s36, s36, 0x100
	s_addc_u32 s37, s37, 0
	s_cmp_ge_u32 s56, s47
	s_mov_b32 s34, s56
	s_cbranch_scc0 .LBB0_342
	s_and_b64 vcc, exec, s[24:25]
	s_cbranch_vccz .LBB0_345
	s_barrier

; __device__ __forceinline__ int tid_fresh() { int t = threadIdx.x; asm volatile("" : "+v"(t)); return t; }
; #define PG8_STAGE(bufoff, gbase, voff) do { _Pragma("unroll") for (int _i = 0; _i < 2; ++_i) \
;         __builtin_amdgcn_global_load_lds((const unsigned*)((const char*)(gbase) + (voff)[_i]), (LAS unsigned*)(lds + (bufoff) + ldsw + _i * 8192), 16, 0, 0); } while (0)
; template <class Epi>
; __device__ __forceinline__ void gemm_phase(LAS unsigned char* lds, const Gemm g, const StaticOrder& S, const Epi& E) {
;     const int tid = tid_fresh(), wid = __builtin_amdgcn_readfirstlane(tid >> 6), lane = tid & 63, wr = wid >> 2, wc = wid & 3, fr = lane & 15, fq = lane >> 4;
;     const int K = g.K, nt = K / BK, lda = g.lda;
;     unsigned voffA[2], voffB[2];
; #pragma unroll
;     for (int i = 0; i < 2; ++i) { int R, C; stage_rc(tid * 16 + i * 8192, R, C); const int Rb = Epi::PERM ? ((R & ~31) + perm32(R & 31)) : R;
;         voffA[i] = (unsigned)(R * lda + C) * 2u; voffB[i] = (unsigned)(Rb * K + C) * 2u; }
;     const size_t kstep = (size_t)(BK * 2);
;     const size_t hA = (size_t)HALF * lda * 2, hB = (size_t)HALF * K * 2;
;     const size_t tA = 2 * hA, tB = 2 * hB;
;     const unsigned ldsw = (unsigned)wid * 1024u;
;     const int aoff = lds_byte(wr * 64 + fr, fq * 8), boff = lds_byte(wc * 32 + fr, fq * 8);
;     ...
;     Unit cur, nxt; int ui = 0;
;     if (!S.next(0, cur)) return;
;     f32x4 acc[2][2][4][2];
; #pragma unroll
;     for (int a = 0; a < 2; ++a)
; #pragma unroll
;         for (int b = 0; b < 2; ++b)
; #pragma unroll
;             for (int m = 0; m < 4; ++m)
; #pragma unroll
;                 for (int n = 0; n < 2; ++n) acc[a][b][m][n] = (f32x4){0.f, 0.f, 0.f, 0.f};
;     bf16x8 At[4][2], B0[2][2], B1[2][2];
;     const char* cA = (const char*)g.A + (size_t)cur.pm * tA + (g.agrp ? (size_t)(cur.pn >> 1) * 1024 : 0);
;     const char* cB = (const char*)g.Bt + (size_t)cur.pn * tB;
;     PG8_STAGE(PG8_SB(0, 0), cB, voffB); PG8_STAGE(PG8_SB(0, 1), cB + hB, voffB); PG8_STAGE(PG8_SA(0, 0), cA, voffA); PG8_STAGE(PG8_SA(0, 1), cA + hA, voffA);
.LBB0_418:
	s_andn2_b64 vcc, exec, s[6:7]
	s_cbranch_vccnz .LBB0_634
	v_ashrrev_i32_e32 v1, 31, v12
	v_lshrrev_b32_e32 v1, 26, v1
	v_add_u32_e32 v1, v12, v1
	v_ashrrev_i32_e32 v13, 6, v1
	v_bfe_i32 v1, v12, 27, 1
	v_lshlrev_b32_e32 v0, 4, v12
	v_lshrrev_b32_e32 v1, 22, v1
	v_add_u32_e32 v1, v0, v1
	v_and_b32_e32 v1, 0xfffffc00, v1
	v_sub_u32_e32 v1, v0, v1
	v_lshrrev_b32_e32 v2, 4, v1
	v_bitop3_b32 v2, v2, v1, 32 bitop3:0x6c
	v_ashrrev_i32_e32 v1, 31, v1
	v_lshrrev_b32_e32 v1, 26, v1
	v_add_u32_e32 v1, v2, v1
	s_waitcnt vmcnt(4)
	v_ashrrev_i32_e32 v14, 6, v1
	v_lshlrev_b32_e32 v3, 3, v13
	v_mul_i32_i24_e32 v4, 64, v14
	v_and_b32_e32 v3, -16, v3
	v_sub_u32_e32 v2, v2, v4
	v_add_u32_e32 v1, v14, v3
	v_lshlrev_b32_e32 v3, 5, v13
	v_ashrrev_i16_sdwa v2, v203, sext(v2) dst_sel:DWORD dst_unused:UNUSED_PAD src0_sel:DWORD src1_sel:BYTE_0
	v_and_b32_e32 v3, 32, v3
	v_bfe_i32 v15, v2, 0, 16
	v_add_u32_e32 v2, v3, v15
	v_lshlrev_b32_e32 v3, 1, v1
	v_lshrrev_b32_e32 v4, 2, v1
	v_and_b32_e32 v5, 3, v14
	s_mov_b32 s7, 0x7fffffe0
	v_and_b32_e32 v3, 24, v3
	v_and_b32_e32 v4, 4, v4
	v_and_or_b32 v5, v1, s7, v5
	v_or3_b32 v3, v5, v4, v3
	v_lshlrev_b32_e32 v1, 12, v1
	v_lshl_add_u32 v160, v2, 1, v1
	v_mul_lo_u32 v1, v3, s20
	v_add_u32_e32 v0, 0x2000, v0
	v_add_lshl_u32 v168, v1, v2, 1
	v_ashrrev_i32_e32 v1, 31, v0
	v_lshrrev_b32_e32 v1, 22, v1
	v_add_u32_e32 v1, v0, v1
	v_ashrrev_i32_e32 v16, 10, v1
	v_mul_i32_i24_e32 v1, 0x400, v16
	v_sub_u32_e32 v0, v0, v1
	v_lshrrev_b32_e32 v1, 4, v0
	v_bitop3_b32 v0, v1, v0, 32 bitop3:0x6c
	v_ashrrev_i32_e32 v2, 31, v0
	v_lshrrev_b32_e32 v2, 26, v2
	v_lshlrev_b32_e32 v1, 3, v16
	v_add_u32_e32 v2, v0, v2
	v_and_b32_e32 v1, -16, v1
	v_ashrrev_i32_e32 v17, 6, v2
	s_ashr_i32 s22, s2, 1
	s_ashr_i32 s6, s24, 6
	v_add_u32_e32 v1, v17, v1
	v_and_b32_e32 v4, 3, v17
	s_ashr_i32 s37, s36, 31
	s_ashr_i32 s23, s22, 31
	v_and_or_b32 v4, v1, s7, v4
	s_ashr_i32 s7, s24, 8
	s_lshl_b32 s46, s20, 8
	s_lshl_b32 s47, s20, 9
	s_lshl_b32 s48, s6, 10
	s_lshl_b64 s[18:19], s[36:37], 20
	s_lshl_b64 s[22:23], s[22:23], 10
	s_and_b64 s[26:27], s[10:11], exec
	s_cselect_b32 s21, 0, s23
	s_cselect_b32 s22, 0, s22
	s_ashr_i32 s23, s2, 31
	v_and_b32_e32 v2, 0xc0, v2
	s_mul_i32 s23, s47, s23
	s_mul_hi_u32 s25, s47, s2
	v_sub_u32_e32 v0, v0, v2
	s_add_i32 s25, s25, s23
	s_mul_i32 s23, s47, s2
	v_lshlrev_b32_e32 v3, 5, v16
	v_ashrrev_i16_sdwa v0, v203, sext(v0) dst_sel:DWORD dst_unused:UNUSED_PAD src0_sel:DWORD src1_sel:BYTE_0
	s_add_u32 s38, s8, s23
	v_and_b32_e32 v3, 32, v3
	s_waitcnt vmcnt(3)
	v_bfe_i32 v18, v0, 0, 16
	s_addc_u32 s39, s9, s25
	s_add_i32 s49, s48, 0
	v_add_u32_e32 v0, v3, v18
	v_lshlrev_b32_e32 v2, 1, v1
	v_lshrrev_b32_e32 v3, 2, v1
	s_add_i32 m0, s49, 0x10000
	v_and_b32_e32 v2, 24, v2
	v_lshrrev_b32_e32 v128, 3, v167
	v_and_b32_e32 v129, 7, v167
	v_xor_b32_e32 v129, v129, v128
	v_lshlrev_b32_e32 v129, 4, v129
	v_lshl_add_u32 v130, s6, 3, v128
	v_lshl_add_u32 v160, v130, 12, v129
	v_add_u32_e32 v248, 0x40000, v160
	v_mov_b32_e32 v131, s6
	v_and_b32_e32 v132, -4, v131
	v_lshlrev_b32_e32 v132, 3, v132
	v_and_b32_e32 v133, 1, v131
	v_lshl_add_u32 v132, v133, 4, v132
	v_and_b32_e32 v133, 2, v131
	v_lshl_add_u32 v132, v133, 1, v132
	v_and_b32_e32 v133, 4, v128
	v_lshl_add_u32 v132, v133, 1, v132
	v_and_b32_e32 v133, 3, v128
	v_add_u32_e32 v132, v132, v133
	v_mov_b32_e32 v134, s20
	v_lshlrev_b32_e32 v134, 1, v134
	v_mul_lo_u32 v135, v132, v134
	v_add_u32_e32 v168, v135, v129
	v_lshl_add_u32 v249, v134, 6, v168
	v_and_b32_e32 v128, 7, v167
	v_lshrrev_b32_e32 v129, 4, v167
	v_bfe_u32 v130, v167, 3, 1
	v_xor_b32_e32 v129, v129, v128
	v_lshlrev_b32_e32 v128, 7, v128
	v_lshl_add_u32 v128, v130, 10, v128
	v_lshl_add_u32 v250, v129, 4, v128
	v_and_b32_e32 v3, 4, v3
	global_load_lds_dwordx4 v168, s[38:39]
	s_add_i32 m0, s49, 0x12000
	v_or3_b32 v2, v4, v3, v2
	v_lshlrev_b32_e32 v1, 12, v1
	s_add_u32 s23, s14, s18
	v_lshl_add_u32 v162, v0, 1, v1
	v_mov_b32_e32 v162, v248
	v_mul_lo_u32 v1, v2, s20
	s_addc_u32 s25, s15, s19
	v_add_lshl_u32 v164, v1, v0, 1
	v_mov_b32_e32 v164, v249
	s_add_u32 s18, s38, s46
	global_load_lds_dwordx4 v164, s[38:39]
	s_addc_u32 s19, s39, 0
	s_add_i32 m0, s49, 0x14000
	v_mov_b32_e32 v165, v169
	global_load_lds_dwordx4 v168, s[18:19]
	s_add_i32 m0, s49, 0x16000
	s_add_u32 s40, s23, s22
	s_addc_u32 s41, s25, s21
	s_add_i32 s50, s49, 0x2000
	global_load_lds_dwordx4 v164, s[18:19]
	s_mov_b32 m0, s49
	s_add_u32 s22, s40, 0x80000
	global_load_lds_dwordx4 v160, s[40:41]
	s_mov_b32 m0, s50
	s_addc_u32 s23, s41, 0
	s_add_i32 s51, s49, 0x4000
	global_load_lds_dwordx4 v162, s[40:41]
	s_mov_b32 m0, s51
	s_add_i32 s52, s49, 0x6000
	global_load_lds_dwordx4 v160, s[22:23]
	s_mov_b32 m0, s52
	v_mov_b32_e32 v161, v169
	global_load_lds_dwordx4 v162, s[22:23]
	v_mov_b32_e32 v163, v169
	s_cmp_eq_u32 s7, 1
	v_lshl_add_u64 v[8:9], s[38:39], 0, v[168:169]
	v_lshl_add_u64 v[4:5], s[38:39], 0, v[164:165]
	v_lshl_add_u64 v[2:3], s[18:19], 0, v[168:169]
	v_lshl_add_u64 v[0:1], s[18:19], 0, v[164:165]
	v_lshl_add_u64 v[6:7], s[40:41], 0, v[160:161]
	s_cselect_b64 s[18:19], -1, 0
	s_cmp_lg_u32 s7, 1
	v_lshl_add_u64 v[10:11], s[40:41], 0, v[162:163]
	s_cbranch_scc1 .LBB0_421
	s_barrier
; #define PG8_STAGE(bufoff, gbase, voff) do { _Pragma("unroll") for (int _i = 0; _i < 2; ++_i) \
;         __builtin_amdgcn_global_load_lds((const unsigned*)((const char*)(gbase) + (voff)[_i]), (LAS unsigned*)(lds + (bufoff) + ldsw + _i * 8192), 16, 0, 0); } while (0)
; #define PG8_WAIT_V(n) asm volatile("s_waitcnt vmcnt(" #n ")" ::: "memory")
; #define PG8_BAR __builtin_amdgcn_s_barrier()
; template <class Epi>
; __device__ __forceinline__ void gemm_phase(LAS unsigned char* lds, const Gemm g, const StaticOrder& S, const Epi& E) {
;     ...
;     const int aoff = lds_byte(wr * 64 + fr, fq * 8), boff = lds_byte(wc * 32 + fr, fq * 8);
;     ...
;     Unit cur, nxt; int ui = 0;
;     if (!S.next(0, cur)) return;
;     f32x4 acc[2][2][4][2];
; #pragma unroll
;     for (int a = 0; a < 2; ++a)
; #pragma unroll
;         for (int b = 0; b < 2; ++b)
; #pragma unroll
;             for (int m = 0; m < 4; ++m)
; #pragma unroll
;                 for (int n = 0; n < 2; ++n) acc[a][b][m][n] = (f32x4){0.f, 0.f, 0.f, 0.f};
;     bf16x8 At[4][2], B0[2][2], B1[2][2];
;     const char* cA = (const char*)g.A + (size_t)cur.pm * tA + (g.agrp ? (size_t)(cur.pn >> 1) * 1024 : 0);
;     const char* cB = (const char*)g.Bt + (size_t)cur.pn * tB;
;     PG8_STAGE(PG8_SB(0, 0), cB, voffB); PG8_STAGE(PG8_SB(0, 1), cB + hB, voffB); PG8_STAGE(PG8_SA(0, 0), cA, voffA); PG8_STAGE(PG8_SA(0, 1), cA + hA, voffA);
;     if (wr == 1) PG8_BAR;
;     PG8_WAIT_V(2); PG8_BAR;
;     PG8_STAGE(PG8_SB(1, 0), cB + kstep, voffB); PG8_STAGE(PG8_SA(1, 0), cA + kstep, voffA); PG8_STAGE(PG8_SB(1, 1), cB + hB + kstep, voffB);
;     PG8_WAIT_V(6); PG8_BAR;
.LBB0_421:
	s_and_b32 s53, s6, 3
	s_lshr_b32 s54, s20, 6
	s_lshl_b32 s6, s7, 13
	s_lshl_b32 s25, s53, 12
	s_add_u32 s20, s74, 0x1b784000
	s_addc_u32 s21, s75, 0
	s_add_u32 s22, s74, 0x4000
	s_addc_u32 s23, s75, 0
	s_add_i32 m0, s49, 0x18000
	v_lshl_add_u64 v[8:9], v[8:9], 0, s[80:81]
	s_waitcnt vmcnt(2)
	s_barrier
	global_load_lds_dwordx4 v[8:9], off
	v_lshl_add_u64 v[4:5], v[4:5], 0, s[80:81]
	s_add_i32 m0, s49, 0x1a000
	s_add_i32 s55, s49, 0x8000
	global_load_lds_dwordx4 v[4:5], off
	v_lshl_add_u64 v[4:5], v[6:7], 0, s[80:81]
	s_mov_b32 m0, s55
	s_add_i32 s56, s49, 0xa000
	global_load_lds_dwordx4 v[4:5], off
	v_lshl_add_u64 v[4:5], v[10:11], 0, s[80:81]
	s_mov_b32 m0, s56
	v_lshl_add_u64 v[2:3], v[2:3], 0, s[80:81]
	global_load_lds_dwordx4 v[4:5], off
	s_add_i32 m0, s49, 0x1c000
	v_lshl_add_u64 v[0:1], v[0:1], 0, s[80:81]
	global_load_lds_dwordx4 v[2:3], off
	s_add_i32 m0, s49, 0x1e000
	s_add_i32 s57, s54, -2
	global_load_lds_dwordx4 v[0:1], off
	v_bfe_u32 v0, v12, 4, 2
	v_and_b32_e32 v1, 15, v12
	v_lshlrev_b32_e32 v3, 4, v0
	v_lshl_or_b32 v206, s7, 6, v1
	v_lshl_or_b32 v1, v1, 6, v3
	v_lshlrev_b32_e32 v3, 2, v12
	v_and_b32_e32 v3, 32, v3
	s_cmpk_lt_u32 s24, 0x100
	v_bitop3_b32 v207, v1, s25, v3 bitop3:0xde
	v_add_u32_e32 v240, 0x10000, v207
	v_lshl_add_u32 v240, s53, 12, v250
	v_add_u32_e32 v240, 0x10000, v240
	v_xor_b32_e32 v252, 64, v240
	v_add_u32_e32 v241, 0x80, v168
	v_add_u32_e32 v242, 0x80, v164
	v_add_u32_e32 v243, 0x80, v160
	v_add_u32_e32 v244, 0x80, v162
	s_cselect_b64 s[24:25], -1, 0
	s_ashr_i32 s59, s44, 31
	s_ashr_i32 s60, s45, 31
	s_lshr_b32 s61, s42, 5
	s_and_b64 s[4:5], s[4:5], exec
	s_cselect_b32 s63, 2, 3
	s_cselect_b32 s62, 4, 8
	s_lshl_b32 s64, s17, s63
	v_bitop3_b32 v4, v1, s6, v3 bitop3:0xde
	v_cvt_f32_u32_e32 v1, s64
	v_lshlrev_b32_e32 v2, 3, v0
	v_cmp_eq_u32_e64 s[4:5], 0, v0
	v_lshlrev_b32_e32 v0, 5, v0
	v_rcp_iflag_f32_e32 v3, v1
	v_mov_b32_e32 v1, v169
	v_lshl_add_u64 v[174:175], s[0:1], 0, v[0:1]
	v_lshlrev_b32_e32 v0, 15, v13
	v_mul_f32_e32 v3, 0x4f7ffffe, v3
	v_cvt_u32_f32_e32 v3, v3
	v_and_b32_e32 v0, 0xffff0000, v0
	v_lshl_add_u32 v0, v14, 12, v0
	v_and_b32_e32 v1, 1, v13
	v_lshl_or_b32 v0, v1, 6, v0
	s_cmp_lg_u64 s[0:1], 0
	v_lshl_add_u32 v176, v15, 1, v0
	v_mov_b32_e32 v176, v160
	v_lshlrev_b32_e32 v0, 15, v16
	s_cselect_b64 s[26:27], -1, 0
	s_sub_i32 s0, 0, s64
	v_readfirstlane_b32 s1, v3
	v_and_b32_e32 v0, 0xffff0000, v0
	s_waitcnt vmcnt(6)
	s_mul_i32 s0, s0, s1
	v_lshl_add_u32 v0, v17, 12, v0
	v_and_b32_e32 v1, 1, v16
	s_mul_hi_u32 s0, s1, s0
	v_lshl_or_b32 v0, v1, 6, v0
	s_mov_b32 s58, 0
	s_mov_b32 s17, s3
	v_lshl_or_b32 v208, s53, 5, v2
	s_add_i32 s65, s1, s0
	v_mov_b32_e32 v177, v169
	v_lshl_add_u32 v178, v18, 1, v0
	v_mov_b32_e32 v178, v162
	v_mov_b32_e32 v179, v169
	v_add_u32_e32 v209, 0, v4
	v_lshl_add_u32 v209, s7, 13, v250
	v_xor_b32_e32 v251, 64, v209
	s_barrier
	s_branch .LBB0_424

; #define PG8_STAGE(bufoff, gbase, voff) do { _Pragma("unroll") for (int _i = 0; _i < 2; ++_i) \
;         __builtin_amdgcn_global_load_lds((const unsigned*)((const char*)(gbase) + (voff)[_i]), (LAS unsigned*)(lds + (bufoff) + ldsw + _i * 8192), 16, 0, 0); } while (0)
; #define PG8_LDA(dst, b, h) do { _Pragma("unroll") for (int m = 0; m < 4; ++m) _Pragma("unroll") for (int k = 0; k < 2; ++k) dst[m][k] = *(const LAS bf16x8*)(lds + PG8_SA(b, h) + aoff + m * 2048 + k * 1024); } while (0)
; #define PG8_LDB(dst, b, h) do { _Pragma("unroll") for (int n = 0; n < 2; ++n) _Pragma("unroll") for (int k = 0; k < 2; ++k) dst[n][k] = *(const LAS bf16x8*)(lds + PG8_SB(b, h) + boff + n * 2048 + k * 1024); } while (0)
; #define PG8_MMA(ai, bj, At, Bt) do { __builtin_amdgcn_s_setprio(1); _Pragma("unroll") for (int m = 0; m < 4; ++m) _Pragma("unroll") for (int n = 0; n < 2; ++n) _Pragma("unroll") for (int k = 0; k < 2; ++k) \
;         acc[ai][bj][m][n] = __builtin_amdgcn_mfma_f32_16x16x32_bf16(Bt[n][k], At[m][k], acc[ai][bj][m][n], 0, 0, 0); __builtin_amdgcn_s_setprio(0); } while (0)
; #define PG8_WAIT_V(n) asm volatile("s_waitcnt vmcnt(" #n ")" ::: "memory")
; #define PG8_WAIT_L(n) asm volatile("s_waitcnt lgkmcnt(" #n ")" ::: "memory")
; #define PG8_BAR __builtin_amdgcn_s_barrier()
; #define PG8_SCHED __builtin_amdgcn_sched_barrier(0)
; template <class Epi>
; __device__ __forceinline__ void gemm_phase(LAS unsigned char* lds, const Gemm g, const StaticOrder& S, const Epi& E) {
;     ...
;             PG8_LDB(B0, 0, 0); PG8_LDB(B1, 0, 1); PG8_SCHED; PG8_LDA(At, 0, 0); PG8_STAGE(PG8_SA(1, 1), a1 + hA, voffA);
;             PG8_WAIT_V(8); PG8_WAIT_L(0); PG8_BAR; PG8_MMA(0, 0, At, B0); PG8_MMA(0, 1, At, B1); PG8_BAR; PG8_SCHED;
;             PG8_LDA(At, 0, 1); PG8_STAGE(PG8_SB(0, 0), b2, voffB); PG8_STAGE(PG8_SB(0, 1), b2 + hB, voffB); PG8_STAGE(PG8_SA(0, 0), a2, voffA);
;             PG8_WAIT_V(8); PG8_WAIT_L(0); PG8_BAR; PG8_MMA(1, 0, At, B0); PG8_MMA(1, 1, At, B1); PG8_BAR; PG8_SCHED;
.LBB0_431:
	s_add_i32 m0, s49, 0xc000
	ds_read_b128 v[128:131], v240
	ds_read_b128 v[132:135], v252
	ds_read_b128 v[136:139], v240 offset:2048
	ds_read_b128 v[140:143], v252 offset:2048
	ds_read_b128 v[144:147], v240 offset:16384
	ds_read_b128 v[148:151], v252 offset:16384
	ds_read_b128 v[152:155], v240 offset:18432
	ds_read_b128 v[156:159], v252 offset:18432
	ds_read_b128 v[180:183], v209
	ds_read_b128 v[184:187], v251
	ds_read_b128 v[188:191], v209 offset:2048
	ds_read_b128 v[192:195], v251 offset:2048
	ds_read_b128 v[210:213], v209 offset:4096
	ds_read_b128 v[214:217], v251 offset:4096
	ds_read_b128 v[218:221], v209 offset:6144
	ds_read_b128 v[222:225], v251 offset:6144
	global_load_lds_dwordx4 v176, s[0:1]
	s_add_i32 m0, s49, 0xe000
	s_nop 0
	global_load_lds_dwordx4 v178, s[0:1]
	s_add_i32 s40, s37, 2
	s_add_u32 s38, s0, 0xfff80080
	s_addc_u32 s39, s1, -1
	s_add_i32 s41, 0, 0x10000
	s_cmp_eq_u32 s57, s37
	s_cselect_b32 s39, s31, s39
	s_cselect_b32 s38, s30, s38
	s_cselect_b32 s69, s35, s33
	s_cselect_b32 s68, s34, s29
	s_add_i32 s37, 0, 0x14000
	s_waitcnt vmcnt(8)
	s_waitcnt lgkmcnt(0)
	s_barrier
	s_setprio 1
	s_waitcnt lgkmcnt(0)
	v_mfma_f32_16x16x32_bf16 v[124:127], v[128:131], v[180:183], v[124:127]
	v_mfma_f32_16x16x32_bf16 v[120:123], v[136:139], v[180:183], v[120:123]
	v_mfma_f32_16x16x32_bf16 v[108:111], v[128:131], v[188:191], v[108:111]
	v_mfma_f32_16x16x32_bf16 v[104:107], v[136:139], v[188:191], v[104:107]
	v_mfma_f32_16x16x32_bf16 v[92:95], v[128:131], v[210:213], v[92:95]
	v_mfma_f32_16x16x32_bf16 v[88:91], v[136:139], v[210:213], v[88:91]
	v_mfma_f32_16x16x32_bf16 v[76:79], v[128:131], v[218:221], v[76:79]
	v_mfma_f32_16x16x32_bf16 v[72:75], v[136:139], v[218:221], v[72:75]
	v_mfma_f32_16x16x32_bf16 v[124:127], v[132:135], v[184:187], v[124:127]
	v_mfma_f32_16x16x32_bf16 v[120:123], v[140:143], v[184:187], v[120:123]
	v_mfma_f32_16x16x32_bf16 v[108:111], v[132:135], v[192:195], v[108:111]
	v_mfma_f32_16x16x32_bf16 v[104:107], v[140:143], v[192:195], v[104:107]
	v_mfma_f32_16x16x32_bf16 v[92:95], v[132:135], v[214:217], v[92:95]
	v_mfma_f32_16x16x32_bf16 v[88:91], v[140:143], v[214:217], v[88:91]
	v_mfma_f32_16x16x32_bf16 v[76:79], v[132:135], v[222:225], v[76:79]
	v_mfma_f32_16x16x32_bf16 v[72:75], v[140:143], v[222:225], v[72:75]
	s_setprio 0
	s_setprio 1
	v_mfma_f32_16x16x32_bf16 v[116:119], v[144:147], v[180:183], v[116:119]
	v_mfma_f32_16x16x32_bf16 v[112:115], v[152:155], v[180:183], v[112:115]
	v_mfma_f32_16x16x32_bf16 v[100:103], v[144:147], v[188:191], v[100:103]
	v_mfma_f32_16x16x32_bf16 v[96:99], v[152:155], v[188:191], v[96:99]
	v_mfma_f32_16x16x32_bf16 v[84:87], v[144:147], v[210:213], v[84:87]
	v_mfma_f32_16x16x32_bf16 v[80:83], v[152:155], v[210:213], v[80:83]
	v_mfma_f32_16x16x32_bf16 v[68:71], v[144:147], v[218:221], v[68:71]
	v_mfma_f32_16x16x32_bf16 v[64:67], v[152:155], v[218:221], v[64:67]
	v_mfma_f32_16x16x32_bf16 v[116:119], v[148:151], v[184:187], v[116:119]
	v_mfma_f32_16x16x32_bf16 v[112:115], v[156:159], v[184:187], v[112:115]
	v_mfma_f32_16x16x32_bf16 v[100:103], v[148:151], v[192:195], v[100:103]
	v_mfma_f32_16x16x32_bf16 v[96:99], v[156:159], v[192:195], v[96:99]
	v_mfma_f32_16x16x32_bf16 v[84:87], v[148:151], v[214:217], v[84:87]
	v_mfma_f32_16x16x32_bf16 v[80:83], v[156:159], v[214:217], v[80:83]
	v_mfma_f32_16x16x32_bf16 v[68:71], v[148:151], v[222:225], v[68:71]
	v_mfma_f32_16x16x32_bf16 v[64:67], v[156:159], v[222:225], v[64:67]
	s_setprio 0
	s_barrier
	ds_read_b128 v[180:183], v209 offset:16384
	ds_read_b128 v[184:187], v251 offset:16384
	ds_read_b128 v[188:191], v209 offset:18432
	ds_read_b128 v[192:195], v251 offset:18432
	ds_read_b128 v[210:213], v209 offset:20480
	ds_read_b128 v[214:217], v251 offset:20480
	ds_read_b128 v[218:221], v209 offset:22528
	ds_read_b128 v[222:225], v251 offset:22528
	s_add_i32 s41, s41, s48
	s_mov_b32 m0, s41
	s_add_i32 s37, s37, s48
	global_load_lds_dwordx4 v168, s[68:69]
	s_add_i32 m0, s41, 0x2000
	s_nop 0
	global_load_lds_dwordx4 v164, s[68:69]
	s_add_u32 s68, s68, s46
	s_addc_u32 s69, s69, 0
	s_mov_b32 m0, s37
	s_nop 0
	global_load_lds_dwordx4 v168, s[68:69]
	s_add_i32 m0, s37, 0x2000
	s_nop 0
	global_load_lds_dwordx4 v164, s[68:69]
	s_mov_b32 m0, s49
	s_nop 0
	global_load_lds_dwordx4 v160, s[38:39]
	s_mov_b32 m0, s50
	s_nop 0
	global_load_lds_dwordx4 v162, s[38:39]
	s_waitcnt vmcnt(8)
	s_waitcnt lgkmcnt(0)
	s_barrier
	s_setprio 1
	s_waitcnt lgkmcnt(0)
	v_mfma_f32_16x16x32_bf16 v[60:63], v[128:131], v[180:183], v[60:63]
	v_mfma_f32_16x16x32_bf16 v[56:59], v[136:139], v[180:183], v[56:59]
	v_mfma_f32_16x16x32_bf16 v[44:47], v[128:131], v[188:191], v[44:47]
	v_mfma_f32_16x16x32_bf16 v[40:43], v[136:139], v[188:191], v[40:43]
	v_mfma_f32_16x16x32_bf16 v[28:31], v[128:131], v[210:213], v[28:31]
	v_mfma_f32_16x16x32_bf16 v[24:27], v[136:139], v[210:213], v[24:27]
	v_mfma_f32_16x16x32_bf16 v[12:15], v[128:131], v[218:221], v[12:15]
	v_mfma_f32_16x16x32_bf16 v[8:11], v[136:139], v[218:221], v[8:11]
	v_mfma_f32_16x16x32_bf16 v[60:63], v[132:135], v[184:187], v[60:63]
	v_mfma_f32_16x16x32_bf16 v[56:59], v[140:143], v[184:187], v[56:59]
	v_mfma_f32_16x16x32_bf16 v[44:47], v[132:135], v[192:195], v[44:47]
	v_mfma_f32_16x16x32_bf16 v[40:43], v[140:143], v[192:195], v[40:43]
	v_mfma_f32_16x16x32_bf16 v[28:31], v[132:135], v[214:217], v[28:31]
	v_mfma_f32_16x16x32_bf16 v[24:27], v[140:143], v[214:217], v[24:27]
	v_mfma_f32_16x16x32_bf16 v[12:15], v[132:135], v[222:225], v[12:15]
	v_mfma_f32_16x16x32_bf16 v[8:11], v[140:143], v[222:225], v[8:11]
	s_setprio 0
	s_setprio 1
	v_mfma_f32_16x16x32_bf16 v[52:55], v[144:147], v[180:183], v[52:55]
	v_mfma_f32_16x16x32_bf16 v[48:51], v[152:155], v[180:183], v[48:51]
	v_mfma_f32_16x16x32_bf16 v[36:39], v[144:147], v[188:191], v[36:39]
	v_mfma_f32_16x16x32_bf16 v[32:35], v[152:155], v[188:191], v[32:35]
	v_mfma_f32_16x16x32_bf16 v[20:23], v[144:147], v[210:213], v[20:23]
	v_mfma_f32_16x16x32_bf16 v[16:19], v[152:155], v[210:213], v[16:19]
	v_mfma_f32_16x16x32_bf16 v[4:7], v[144:147], v[218:221], v[4:7]
	v_mfma_f32_16x16x32_bf16 v[0:3], v[152:155], v[218:221], v[0:3]
	v_mfma_f32_16x16x32_bf16 v[52:55], v[148:151], v[184:187], v[52:55]
	v_mfma_f32_16x16x32_bf16 v[48:51], v[156:159], v[184:187], v[48:51]
	v_mfma_f32_16x16x32_bf16 v[36:39], v[148:151], v[192:195], v[36:39]
	v_mfma_f32_16x16x32_bf16 v[32:35], v[156:159], v[192:195], v[32:35]
	v_mfma_f32_16x16x32_bf16 v[20:23], v[148:151], v[214:217], v[20:23]
	v_mfma_f32_16x16x32_bf16 v[16:19], v[156:159], v[214:217], v[16:19]
	v_mfma_f32_16x16x32_bf16 v[4:7], v[148:151], v[222:225], v[4:7]
	v_mfma_f32_16x16x32_bf16 v[0:3], v[156:159], v[222:225], v[0:3]
	s_setprio 0
	s_barrier
; #define PG8_STAGE(bufoff, gbase, voff) do { _Pragma("unroll") for (int _i = 0; _i < 2; ++_i) \
;         __builtin_amdgcn_global_load_lds((const unsigned*)((const char*)(gbase) + (voff)[_i]), (LAS unsigned*)(lds + (bufoff) + ldsw + _i * 8192), 16, 0, 0); } while (0)
; #define PG8_LDA(dst, b, h) do { _Pragma("unroll") for (int m = 0; m < 4; ++m) _Pragma("unroll") for (int k = 0; k < 2; ++k) dst[m][k] = *(const LAS bf16x8*)(lds + PG8_SA(b, h) + aoff + m * 2048 + k * 1024); } while (0)
; #define PG8_LDB(dst, b, h) do { _Pragma("unroll") for (int n = 0; n < 2; ++n) _Pragma("unroll") for (int k = 0; k < 2; ++k) dst[n][k] = *(const LAS bf16x8*)(lds + PG8_SB(b, h) + boff + n * 2048 + k * 1024); } while (0)
; #define PG8_MMA(ai, bj, At, Bt) do { __builtin_amdgcn_s_setprio(1); _Pragma("unroll") for (int m = 0; m < 4; ++m) _Pragma("unroll") for (int n = 0; n < 2; ++n) _Pragma("unroll") for (int k = 0; k < 2; ++k) \
;         acc[ai][bj][m][n] = __builtin_amdgcn_mfma_f32_16x16x32_bf16(Bt[n][k], At[m][k], acc[ai][bj][m][n], 0, 0, 0); __builtin_amdgcn_s_setprio(0); } while (0)
; #define PG8_WAIT_V(n) asm volatile("s_waitcnt vmcnt(" #n ")" ::: "memory")
; #define PG8_WAIT_L(n) asm volatile("s_waitcnt lgkmcnt(" #n ")" ::: "memory")
; #define PG8_BAR __builtin_amdgcn_s_barrier()
; #define PG8_SCHED __builtin_amdgcn_sched_barrier(0)
; template <class Epi>
; __device__ __forceinline__ void gemm_phase(LAS unsigned char* lds, const Gemm g, const StaticOrder& S, const Epi& E) {
;     ...
;             PG8_LDB(B0, 1, 0); PG8_LDB(B1, 1, 1); PG8_SCHED; PG8_LDA(At, 1, 0); PG8_STAGE(PG8_SA(0, 1), a2 + hA, voffA);
;             PG8_WAIT_V(8); PG8_WAIT_L(0); PG8_BAR; PG8_MMA(0, 0, At, B0); PG8_MMA(0, 1, At, B1); PG8_BAR; PG8_SCHED;
;             PG8_LDA(At, 1, 1); PG8_STAGE(PG8_SB(1, 0), b3, voffB); PG8_STAGE(PG8_SB(1, 1), b3 + hB, voffB); PG8_STAGE(PG8_SA(1, 0), a3, voffA);
;             PG8_WAIT_V(8); PG8_WAIT_L(0); PG8_BAR; PG8_MMA(1, 0, At, B0); PG8_MMA(1, 1, At, B1); PG8_BAR; PG8_SCHED;
;         }
	ds_read_b128 v[128:131], v240 offset:32768
	ds_read_b128 v[132:135], v252 offset:32768
	ds_read_b128 v[136:139], v240 offset:34816
	ds_read_b128 v[140:143], v252 offset:34816
	ds_read_b128 v[144:147], v240 offset:49152
	ds_read_b128 v[148:151], v252 offset:49152
	ds_read_b128 v[152:155], v240 offset:51200
	ds_read_b128 v[156:159], v252 offset:51200
	ds_read_b128 v[180:183], v209 offset:32768
	ds_read_b128 v[184:187], v251 offset:32768
	ds_read_b128 v[188:191], v209 offset:34816
	ds_read_b128 v[192:195], v251 offset:34816
	ds_read_b128 v[210:213], v209 offset:36864
	ds_read_b128 v[214:217], v251 offset:36864
	ds_read_b128 v[218:221], v209 offset:38912
	ds_read_b128 v[222:225], v251 offset:38912
	s_add_u32 s38, s38, 0x80000
	s_addc_u32 s39, s39, 0
	s_mov_b32 m0, s51
	s_add_i32 s41, 0, 0x18000
	global_load_lds_dwordx4 v160, s[38:39]
	s_mov_b32 m0, s52
	s_nop 0
	global_load_lds_dwordx4 v162, s[38:39]
	s_waitcnt vmcnt(8)
	s_waitcnt lgkmcnt(0)
	s_barrier
	s_setprio 1
	s_waitcnt lgkmcnt(0)
	v_mfma_f32_16x16x32_bf16 v[124:127], v[128:131], v[180:183], v[124:127]
	v_mfma_f32_16x16x32_bf16 v[120:123], v[136:139], v[180:183], v[120:123]
	v_mfma_f32_16x16x32_bf16 v[108:111], v[128:131], v[188:191], v[108:111]
	v_mfma_f32_16x16x32_bf16 v[104:107], v[136:139], v[188:191], v[104:107]
	v_mfma_f32_16x16x32_bf16 v[92:95], v[128:131], v[210:213], v[92:95]
	v_mfma_f32_16x16x32_bf16 v[88:91], v[136:139], v[210:213], v[88:91]
	v_mfma_f32_16x16x32_bf16 v[76:79], v[128:131], v[218:221], v[76:79]
	v_mfma_f32_16x16x32_bf16 v[72:75], v[136:139], v[218:221], v[72:75]
	v_mfma_f32_16x16x32_bf16 v[124:127], v[132:135], v[184:187], v[124:127]
	v_mfma_f32_16x16x32_bf16 v[120:123], v[140:143], v[184:187], v[120:123]
	v_mfma_f32_16x16x32_bf16 v[108:111], v[132:135], v[192:195], v[108:111]
	v_mfma_f32_16x16x32_bf16 v[104:107], v[140:143], v[192:195], v[104:107]
	v_mfma_f32_16x16x32_bf16 v[92:95], v[132:135], v[214:217], v[92:95]
	v_mfma_f32_16x16x32_bf16 v[88:91], v[140:143], v[214:217], v[88:91]
	v_mfma_f32_16x16x32_bf16 v[76:79], v[132:135], v[222:225], v[76:79]
	v_mfma_f32_16x16x32_bf16 v[72:75], v[140:143], v[222:225], v[72:75]
	s_setprio 0
	s_setprio 1
	v_mfma_f32_16x16x32_bf16 v[116:119], v[144:147], v[180:183], v[116:119]
	v_mfma_f32_16x16x32_bf16 v[112:115], v[152:155], v[180:183], v[112:115]
	v_mfma_f32_16x16x32_bf16 v[100:103], v[144:147], v[188:191], v[100:103]
	v_mfma_f32_16x16x32_bf16 v[96:99], v[152:155], v[188:191], v[96:99]
	v_mfma_f32_16x16x32_bf16 v[84:87], v[144:147], v[210:213], v[84:87]
	v_mfma_f32_16x16x32_bf16 v[80:83], v[152:155], v[210:213], v[80:83]
	v_mfma_f32_16x16x32_bf16 v[68:71], v[144:147], v[218:221], v[68:71]
	v_mfma_f32_16x16x32_bf16 v[64:67], v[152:155], v[218:221], v[64:67]
	v_mfma_f32_16x16x32_bf16 v[116:119], v[148:151], v[184:187], v[116:119]
	v_mfma_f32_16x16x32_bf16 v[112:115], v[156:159], v[184:187], v[112:115]
	v_mfma_f32_16x16x32_bf16 v[100:103], v[148:151], v[192:195], v[100:103]
	v_mfma_f32_16x16x32_bf16 v[96:99], v[156:159], v[192:195], v[96:99]
	v_mfma_f32_16x16x32_bf16 v[84:87], v[148:151], v[214:217], v[84:87]
	v_mfma_f32_16x16x32_bf16 v[80:83], v[156:159], v[214:217], v[80:83]
	v_mfma_f32_16x16x32_bf16 v[68:71], v[148:151], v[222:225], v[68:71]
	v_mfma_f32_16x16x32_bf16 v[64:67], v[156:159], v[222:225], v[64:67]
	s_setprio 0
	s_barrier
	ds_read_b128 v[180:183], v209 offset:49152
	ds_read_b128 v[184:187], v251 offset:49152
	ds_read_b128 v[188:191], v209 offset:51200
	ds_read_b128 v[192:195], v251 offset:51200
	ds_read_b128 v[210:213], v209 offset:53248
	ds_read_b128 v[214:217], v251 offset:53248
	ds_read_b128 v[218:221], v209 offset:55296
	ds_read_b128 v[222:225], v251 offset:55296
	s_add_i32 s41, s41, s48
	s_add_i32 m0, s41, 0x4000
	s_nop 0
	global_load_lds_dwordx4 v241, s[68:69]
	s_add_i32 m0, s41, 0x6000
	s_nop 0
	global_load_lds_dwordx4 v242, s[68:69]
	s_sub_u32 s68, s68, s46
	s_subb_u32 s69, s69, 0
	s_mov_b32 m0, s41
	s_nop 0
	global_load_lds_dwordx4 v241, s[68:69]
	s_add_i32 m0, s41, 0x2000
	s_nop 0
	global_load_lds_dwordx4 v242, s[68:69]
	s_sub_u32 s38, s38, 0x80000
	s_subb_u32 s39, s39, 0
	s_mov_b32 m0, s55
	s_nop 0
	global_load_lds_dwordx4 v243, s[38:39]
	s_mov_b32 m0, s56
	s_nop 0
	global_load_lds_dwordx4 v244, s[38:39]
	s_waitcnt vmcnt(8)
	s_waitcnt lgkmcnt(0)
	s_barrier
	s_setprio 1
	s_waitcnt lgkmcnt(0)
	v_mfma_f32_16x16x32_bf16 v[60:63], v[128:131], v[180:183], v[60:63]
	v_mfma_f32_16x16x32_bf16 v[56:59], v[136:139], v[180:183], v[56:59]
	v_mfma_f32_16x16x32_bf16 v[44:47], v[128:131], v[188:191], v[44:47]
	v_mfma_f32_16x16x32_bf16 v[40:43], v[136:139], v[188:191], v[40:43]
	v_mfma_f32_16x16x32_bf16 v[28:31], v[128:131], v[210:213], v[28:31]
	v_mfma_f32_16x16x32_bf16 v[24:27], v[136:139], v[210:213], v[24:27]
	v_mfma_f32_16x16x32_bf16 v[12:15], v[128:131], v[218:221], v[12:15]
	v_mfma_f32_16x16x32_bf16 v[8:11], v[136:139], v[218:221], v[8:11]
	v_mfma_f32_16x16x32_bf16 v[60:63], v[132:135], v[184:187], v[60:63]
	v_mfma_f32_16x16x32_bf16 v[56:59], v[140:143], v[184:187], v[56:59]
	v_mfma_f32_16x16x32_bf16 v[44:47], v[132:135], v[192:195], v[44:47]
	v_mfma_f32_16x16x32_bf16 v[40:43], v[140:143], v[192:195], v[40:43]
	v_mfma_f32_16x16x32_bf16 v[28:31], v[132:135], v[214:217], v[28:31]
	v_mfma_f32_16x16x32_bf16 v[24:27], v[140:143], v[214:217], v[24:27]
	v_mfma_f32_16x16x32_bf16 v[12:15], v[132:135], v[222:225], v[12:15]
	v_mfma_f32_16x16x32_bf16 v[8:11], v[140:143], v[222:225], v[8:11]
	s_setprio 0
	s_setprio 1
	v_mfma_f32_16x16x32_bf16 v[52:55], v[144:147], v[180:183], v[52:55]
	v_mfma_f32_16x16x32_bf16 v[48:51], v[152:155], v[180:183], v[48:51]
	v_mfma_f32_16x16x32_bf16 v[36:39], v[144:147], v[188:191], v[36:39]
	v_mfma_f32_16x16x32_bf16 v[32:35], v[152:155], v[188:191], v[32:35]
	v_mfma_f32_16x16x32_bf16 v[20:23], v[144:147], v[210:213], v[20:23]
	v_mfma_f32_16x16x32_bf16 v[16:19], v[152:155], v[210:213], v[16:19]
	v_mfma_f32_16x16x32_bf16 v[4:7], v[144:147], v[218:221], v[4:7]
	v_mfma_f32_16x16x32_bf16 v[0:3], v[152:155], v[218:221], v[0:3]
	v_mfma_f32_16x16x32_bf16 v[52:55], v[148:151], v[184:187], v[52:55]
	v_mfma_f32_16x16x32_bf16 v[48:51], v[156:159], v[184:187], v[48:51]
	v_mfma_f32_16x16x32_bf16 v[36:39], v[148:151], v[192:195], v[36:39]
	v_mfma_f32_16x16x32_bf16 v[32:35], v[156:159], v[192:195], v[32:35]
	v_mfma_f32_16x16x32_bf16 v[20:23], v[148:151], v[214:217], v[20:23]
	v_mfma_f32_16x16x32_bf16 v[16:19], v[156:159], v[214:217], v[16:19]
	v_mfma_f32_16x16x32_bf16 v[4:7], v[148:151], v[222:225], v[4:7]
	v_mfma_f32_16x16x32_bf16 v[0:3], v[156:159], v[222:225], v[0:3]
	s_setprio 0
	s_barrier
	s_add_u32 s0, s0, 0x100
	s_addc_u32 s1, s1, 0
	s_add_u32 s29, s29, 0x100
	s_addc_u32 s33, s33, 0
	s_cmp_ge_u32 s40, s54
	s_mov_b32 s37, s40
	s_cbranch_scc0 .LBB0_431
	s_and_b64 vcc, exec, s[24:25]
	s_cbranch_vccz .LBB0_434
	s_barrier

; __global__ void __launch_bounds__(512, 2) fwd_kernel(Params p_unused) {
	.amdhsa_kernel _Z10fwd_kernel6Params
		.amdhsa_group_segment_fixed_size 0
		.amdhsa_private_segment_fixed_size 0
		.amdhsa_kernarg_size 408
		.amdhsa_user_sgpr_count 2
		.amdhsa_user_sgpr_dispatch_ptr 0
		.amdhsa_user_sgpr_queue_ptr 0
		.amdhsa_user_sgpr_kernarg_segment_ptr 1
		.amdhsa_user_sgpr_dispatch_id 0
		.amdhsa_user_sgpr_kernarg_preload_length 0
		.amdhsa_user_sgpr_kernarg_preload_offset 0
		.amdhsa_user_sgpr_private_segment_size 0
		.amdhsa_uses_dynamic_stack 0
		.amdhsa_enable_private_segment 0
		.amdhsa_system_sgpr_workgroup_id_x 1
		.amdhsa_system_sgpr_workgroup_id_y 0
		.amdhsa_system_sgpr_workgroup_id_z 0
		.amdhsa_system_sgpr_workgroup_info 0
		.amdhsa_system_vgpr_workitem_id 2
		.amdhsa_next_free_vgpr 256
		.amdhsa_next_free_sgpr 100
		.amdhsa_accum_offset 256
		.amdhsa_reserve_vcc 1
		.amdhsa_float_round_mode_32 0
		.amdhsa_float_round_mode_16_64 0
		.amdhsa_float_denorm_mode_32 3
		.amdhsa_float_denorm_mode_16_64 3
		.amdhsa_dx10_clamp 1
		.amdhsa_ieee_mode 1
		.amdhsa_fp16_overflow 0
		.amdhsa_tg_split 0
		.amdhsa_exception_fp_ieee_invalid_op 0
		.amdhsa_exception_fp_denorm_src 0
		.amdhsa_exception_fp_ieee_div_zero 0
		.amdhsa_exception_fp_ieee_overflow 0
		.amdhsa_exception_fp_ieee_underflow 0
		.amdhsa_exception_fp_ieee_inexact 0
		.amdhsa_exception_int_div_zero 0
	.end_amdhsa_kernel

; __global__ void __launch_bounds__(512, 2) fwd_kernel(Params p_unused) {
amdhsa.kernels:
  - .agpr_count:     0
    .args:
      - .offset:         0
        .size:           152
        .value_kind:     by_value
      - .offset:         152
        .size:           4
        .value_kind:     hidden_block_count_x
      - .offset:         156
        .size:           4
        .value_kind:     hidden_block_count_y
      - .offset:         160
        .size:           4
        .value_kind:     hidden_block_count_z
      - .offset:         164
        .size:           2
        .value_kind:     hidden_group_size_x
      - .offset:         166
        .size:           2
        .value_kind:     hidden_group_size_y
      - .offset:         168
        .size:           2
        .value_kind:     hidden_group_size_z
      - .offset:         170
        .size:           2
        .value_kind:     hidden_remainder_x
      - .offset:         172
        .size:           2
        .value_kind:     hidden_remainder_y
      - .offset:         174
        .size:           2
        .value_kind:     hidden_remainder_z
      - .offset:         192
        .size:           8
        .value_kind:     hidden_global_offset_x
      - .offset:         200
        .size:           8
        .value_kind:     hidden_global_offset_y
      - .offset:         208
        .size:           8
        .value_kind:     hidden_global_offset_z
      - .offset:         216
        .size:           2
        .value_kind:     hidden_grid_dims
      - .offset:         240
        .size:           8
        .value_kind:     hidden_multigrid_sync_arg
      - .offset:         272
        .size:           4
        .value_kind:     hidden_dynamic_lds_size
    .group_segment_fixed_size: 0
    .kernarg_segment_align: 8
    .kernarg_segment_size: 408
    .language:       OpenCL C
    .language_version:
      - 2
      - 0
    .max_flat_workgroup_size: 512
    .name:           _Z10fwd_kernel6Params
    .private_segment_fixed_size: 0
    .sgpr_count:     106
    .sgpr_spill_count: 119
    .symbol:         _Z10fwd_kernel6Params.kd
    .uniform_work_group_size: 1
    .uses_dynamic_stack: false
    .vgpr_count:     256
    .vgpr_spill_count: 0
    .wavefront_size: 64
